# post phase loop unrolled x2 (20 loads in flight per wait); ret_kv counted vmcnt; ret_out wait moved above first store
# speedup vs baseline: 1.0063x; 1.0063x over previous
.LBB0_380:
	s_or_b64 exec, exec, s[68:69]
	v_readlane_b32 s0, v252, 11
	v_readlane_b32 s1, v252, 12
	s_xor_b64 s[68:69], s[0:1], -1
	s_xor_b64 s[0:1], s[50:51], -1
	v_writelane_b32 v252, s0, 21
	s_waitcnt lgkmcnt(0)
	s_barrier
	v_writelane_b32 v252, s1, 22
	s_mov_b32 s0, s45
	s_add_i32 s0, s0, 0x200e8
	v_mov_b32_e32 v0, s0
	s_mov_b32 s0, 0
	ds_read_b64 v[2:3], v0
	s_add_i32 s0, s0, 0x200e8
	v_mov_b32_e32 v0, s0
	s_mov_b32 s0, 0
	ds_read_b64 v[4:5], v0
	s_add_i32 s0, s0, 0x200e8
	v_mov_b32_e32 v0, s0
	ds_read_b64 v[6:7], v0
	s_mov_b32 s5, 0
	v_mov_b32_e32 v0, v200
	v_readlane_b32 s4, v252, 0
	s_waitcnt lgkmcnt(0)
	v_readfirstlane_b32 s1, v3
	v_readfirstlane_b32 s0, v2
	v_readfirstlane_b32 s3, v5
	v_readfirstlane_b32 s2, v4
	v_readfirstlane_b32 s6, v7
	s_cmpk_gt_i32 s4, 0x7ff
	v_readfirstlane_b32 s7, v6
	s_cbranch_scc1 .LBB0_385
	s_add_u32 s0, s0, 0x8bf0000
	s_addc_u32 s1, s1, 0
	s_add_u32 s8, s7, 0x10000
	s_addc_u32 s9, s6, 0
	s_ashr_i32 s6, s4, 8
	s_ashr_i32 s7, s6, 31
	s_lshl_b32 s10, s4, 6
	v_ashrrev_i32_e32 v42, 3, v0
	s_lshl_b64 s[6:7], s[6:7], 12
	s_and_b32 s10, s10, 0xfc0
	v_ashrrev_i32_e32 v43, 31, v42
	s_or_b32 s6, s6, s10
	v_lshl_add_u64 v[2:3], s[6:7], 0, v[42:43]
	v_mov_b64_e32 v[4:5], s[0:1]
	v_mad_u64_u32 v[4:5], s[6:7], v2, s95, v[4:5]
	v_add_u32_e32 v2, s10, v42
	v_mad_i32_i24 v5, v3, s95, v5
	s_lshl_b32 s6, s4, 2
	v_ashrrev_i32_e32 v3, 31, v2
	v_and_b32_e32 v26, 7, v0
	s_and_b32 s44, s6, 0x300
	v_lshlrev_b64 v[2:3], 8, v[2:3]
	v_lshl_add_u64 v[18:19], v[4:5], 0, s[44:45]
	v_lshl_add_u64 v[2:3], s[8:9], 0, v[2:3]
	v_lshlrev_b32_e32 v44, 5, v26
	v_mov_b32_e32 v45, v1
	v_lshlrev_b32_e32 v46, 4, v26
	v_mov_b32_e32 v47, v1
	v_lshl_add_u64 v[6:7], v[2:3], 0, v[44:45]
	v_lshl_add_u64 v[14:15], v[18:19], 0, v[46:47]
	v_lshl_add_u64 v[22:23], v[18:19], 0, v[44:45]
	flat_load_dwordx4 v[2:5], v[6:7]
	s_nop 0
	flat_load_dwordx4 v[6:9], v[6:7] offset:16
	s_nop 0
	flat_load_dwordx4 v[10:13], v[14:15] offset:1024
	s_nop 0
	flat_load_dwordx4 v[14:17], v[14:15] offset:1152
	s_nop 0
	flat_load_dwordx4 v[18:21], v[22:23] offset:2048
	s_nop 0
	flat_load_dwordx4 v[22:25], v[22:23] offset:2064
	v_sub_u32_e32 v28, 63, v42
	s_movk_i32 s6, 0x120
	v_cvt_f32_i32_e32 v47, v28
	v_mul_lo_u32 v28, v42, s6
	v_add_u32_e32 v56, s5, v28
	v_lshrrev_b32_e32 v28, 1, v0
	v_lshrrev_b32_e32 v29, 2, v0
	v_and_b32_e32 v28, 24, v28
	v_and_or_b32 v29, v29, 3, v28
	v_mov_b32_e32 v30, s5
	v_ashrrev_i32_e32 v27, 6, v0
	v_lshl_add_u64 v[48:49], s[8:9], 0, v[44:45]
	v_mad_u32_u24 v45, v29, s6, v30
	v_lshlrev_b32_e32 v29, 3, v0
	v_lshlrev_b32_e32 v0, 8, v0
	v_and_b32_e32 v0, 0xf00, v0
	v_lshlrev_b32_e32 v32, 4, v27
	v_lshl_add_u64 v[30:31], s[2:3], 0, v[0:1]
	v_ashrrev_i32_e32 v33, 31, v32
	v_and_b32_e32 v57, 24, v29
	v_lshl_add_u64 v[30:31], v[32:33], 1, v[30:31]
	v_mov_b32_e32 v29, v1
	v_lshl_add_u64 v[28:29], v[30:31], 0, v[28:29]
	s_mov_b64 s[2:3], 0x4bf0000
	v_lshlrev_b32_e32 v26, 3, v26
	v_lshl_add_u32 v34, v27, 5, v45
	v_lshl_add_u64 v[50:51], v[28:29], 0, s[2:3]
	s_add_i32 s2, s36, s4
	s_lshl_b32 s6, s2, 6
	s_lshl_b32 s7, s2, 1
	v_add_u32_e32 v58, v56, v46
	v_lshlrev_b32_e32 v0, 1, v26
	v_add_u32_e32 v59, v34, v57
	s_waitcnt vmcnt(0)
	s_branch .LBB0_383
.LBB0_382:
	v_add_u32_e32 v60, v45, v57
	s_waitcnt lgkmcnt(0)
	s_barrier
	ds_read_b64_tr_b16 v[26:27], v59
	ds_read_b64_tr_b16 v[28:29], v59 offset:1152
	ds_read_b64_tr_b16 v[30:31], v59 offset:9216
	ds_read_b64_tr_b16 v[32:33], v59 offset:10368
	ds_read_b64_tr_b16 v[34:35], v60 offset:18432
	ds_read_b64_tr_b16 v[36:37], v60 offset:19584
	ds_read_b64_tr_b16 v[38:39], v60 offset:27648
	ds_read_b64_tr_b16 v[40:41], v60 offset:28800
	s_waitcnt lgkmcnt(0)
	v_mfma_f32_16x16x32_bf16 v[34:37], v[26:29], v[34:37], 0
	s_ashr_i32 s5, s4, 31
	s_lshl_b64 s[4:5], s[4:5], 15
	v_lshl_add_u64 v[52:53], v[50:51], 0, s[4:5]
	v_mfma_f32_16x16x32_bf16 v[34:37], v[30:33], v[38:41], v[34:37]
	s_movk_i32 s4, 0x1000
	v_add_co_u32_e32 v54, vcc, s4, v52
	s_movk_i32 s4, 0x2000
	s_nop 0
	v_addc_co_u32_e32 v55, vcc, 0, v53, vcc
	s_nop 2
	v_cvt_pk_bf16_f32 v34, v34, v35
	v_cvt_pk_bf16_f32 v35, v36, v37
	global_store_dwordx2 v[52:53], v[34:35], off
	ds_read_b64_tr_b16 v[34:35], v60 offset:18464
	ds_read_b64_tr_b16 v[36:37], v60 offset:19616
	ds_read_b64_tr_b16 v[38:39], v60 offset:27680
	ds_read_b64_tr_b16 v[40:41], v60 offset:28832
	s_waitcnt lgkmcnt(0)
	v_mfma_f32_16x16x32_bf16 v[34:37], v[26:29], v[34:37], 0
	s_movk_i32 s5, 0x4000
	s_add_i32 s6, s6, s62
	s_add_i32 s7, s7, s53
	v_mfma_f32_16x16x32_bf16 v[34:37], v[30:33], v[38:41], v[34:37]
	s_nop 7
	v_cvt_pk_bf16_f32 v34, v34, v35
	v_cvt_pk_bf16_f32 v35, v36, v37
	global_store_dwordx2 v[54:55], v[34:35], off
	ds_read_b64_tr_b16 v[34:35], v60 offset:18496
	ds_read_b64_tr_b16 v[36:37], v60 offset:19648
	ds_read_b64_tr_b16 v[38:39], v60 offset:27712
	ds_read_b64_tr_b16 v[40:41], v60 offset:28864
	s_waitcnt lgkmcnt(0)
	v_mfma_f32_16x16x32_bf16 v[34:37], v[26:29], v[34:37], 0
	v_add_co_u32_e32 v54, vcc, s4, v52
	s_movk_i32 s4, 0x3000
	v_mfma_f32_16x16x32_bf16 v[34:37], v[30:33], v[38:41], v[34:37]
	v_addc_co_u32_e32 v55, vcc, 0, v53, vcc
	s_nop 6
	v_cvt_pk_bf16_f32 v34, v34, v35
	v_cvt_pk_bf16_f32 v35, v36, v37
	global_store_dwordx2 v[54:55], v[34:35], off
	ds_read_b64_tr_b16 v[34:35], v60 offset:18528
	ds_read_b64_tr_b16 v[36:37], v60 offset:19680
	ds_read_b64_tr_b16 v[38:39], v60 offset:27744
	ds_read_b64_tr_b16 v[40:41], v60 offset:28896
	s_waitcnt lgkmcnt(0)
	v_mfma_f32_16x16x32_bf16 v[34:37], v[26:29], v[34:37], 0
	v_add_co_u32_e32 v54, vcc, s4, v52
	s_movk_i32 s4, 0x5000
	v_mfma_f32_16x16x32_bf16 v[34:37], v[30:33], v[38:41], v[34:37]
	v_addc_co_u32_e32 v55, vcc, 0, v53, vcc
	s_nop 6
	v_cvt_pk_bf16_f32 v34, v34, v35
	v_cvt_pk_bf16_f32 v35, v36, v37
	global_store_dwordx2 v[54:55], v[34:35], off
	ds_read_b64_tr_b16 v[38:39], v60 offset:18560
	ds_read_b64_tr_b16 v[40:41], v60 offset:19712
	ds_read_b64_tr_b16 v[34:35], v60 offset:27776
	ds_read_b64_tr_b16 v[36:37], v60 offset:28928
	s_waitcnt lgkmcnt(0)
	v_mfma_f32_16x16x32_bf16 v[38:41], v[26:29], v[38:41], 0
	v_add_co_u32_e32 v54, vcc, s5, v52
	v_mfma_f32_16x16x32_bf16 v[34:37], v[30:33], v[34:37], v[38:41]
	s_nop 0
	v_addc_co_u32_e32 v55, vcc, 0, v53, vcc
	s_nop 5
	v_cvt_pk_bf16_f32 v34, v34, v35
	v_cvt_pk_bf16_f32 v35, v36, v37
	global_store_dwordx2 v[54:55], v[34:35], off
	ds_read_b64_tr_b16 v[34:35], v60 offset:18592
	ds_read_b64_tr_b16 v[36:37], v60 offset:19744
	ds_read_b64_tr_b16 v[38:39], v60 offset:27808
	ds_read_b64_tr_b16 v[40:41], v60 offset:28960
	s_waitcnt lgkmcnt(0)
	v_mfma_f32_16x16x32_bf16 v[34:37], v[26:29], v[34:37], 0
	v_add_co_u32_e32 v54, vcc, s4, v52
	s_mov_b32 s4, s8
	v_mfma_f32_16x16x32_bf16 v[34:37], v[30:33], v[38:41], v[34:37]
	v_addc_co_u32_e32 v55, vcc, 0, v53, vcc
	s_nop 6
	v_cvt_pk_bf16_f32 v34, v34, v35
	v_cvt_pk_bf16_f32 v35, v36, v37
	global_store_dwordx2 v[54:55], v[34:35], off
	ds_read_b64_tr_b16 v[34:35], v60 offset:18624
	ds_read_b64_tr_b16 v[36:37], v60 offset:19776
	ds_read_b64_tr_b16 v[38:39], v60 offset:27840
	ds_read_b64_tr_b16 v[40:41], v60 offset:28992
	s_waitcnt lgkmcnt(0)
	v_mfma_f32_16x16x32_bf16 v[34:37], v[26:29], v[34:37], 0
	v_add_co_u32_e32 v54, vcc, s55, v52
	v_mfma_f32_16x16x32_bf16 v[34:37], v[30:33], v[38:41], v[34:37]
	s_nop 0
	v_addc_co_u32_e32 v55, vcc, 0, v53, vcc
	v_add_co_u32_e32 v52, vcc, 0x7000, v52
	s_nop 1
	v_addc_co_u32_e32 v53, vcc, 0, v53, vcc
	s_nop 1
	v_cvt_pk_bf16_f32 v34, v34, v35
	v_cvt_pk_bf16_f32 v35, v36, v37
	global_store_dwordx2 v[54:55], v[34:35], off
	ds_read_b64_tr_b16 v[34:35], v60 offset:18656
	ds_read_b64_tr_b16 v[36:37], v60 offset:19808
	ds_read_b64_tr_b16 v[38:39], v60 offset:27872
	ds_read_b64_tr_b16 v[40:41], v60 offset:29024
	s_waitcnt lgkmcnt(0)
	v_mfma_f32_16x16x32_bf16 v[26:29], v[26:29], v[34:37], 0
	s_andn2_b64 vcc, exec, s[2:3]
	v_mfma_f32_16x16x32_bf16 v[26:29], v[30:33], v[38:41], v[26:29]
	s_nop 7
	v_cvt_pk_bf16_f32 v26, v26, v27
	v_cvt_pk_bf16_f32 v27, v28, v29
	global_store_dwordx2 v[52:53], v[26:27], off
	s_cbranch_vccz .LBB0_385
.LBB0_383:
	s_bfe_u32 s2, s4, 0x20006
	v_cvt_f32_ubyte0_e32 v26, s2
	v_sub_f32_e32 v26, 0xc0a00000, v26
	v_cmp_gt_f32_e32 vcc, s63, v26
	s_and_b64 s[2:3], vcc, exec
	s_cselect_b32 s2, 0xffffffc0, 0
	v_cndmask_b32_e32 v27, 0, v207, vcc
	v_add_f32_e32 v26, v26, v27
	v_exp_f32_e32 v26, v26
	s_waitcnt vmcnt(8) lgkmcnt(0)
	v_cvt_f32_f16_sdwa v29, v3 dst_sel:DWORD dst_unused:UNUSED_PAD src0_sel:WORD_1
	v_cvt_f32_f16_e32 v33, v3
	v_cvt_f32_f16_e32 v32, v2
	v_ldexp_f32 v26, v26, s2
	v_sub_f32_e32 v26, 1.0, v26
	v_log_f32_e32 v26, v26
	v_lshlrev_b32_e32 v34, 16, v14
	v_and_b32_e32 v35, 0xffff0000, v14
	v_and_b32_e32 v27, 0xffff0000, v10
	v_mul_f32_e32 v26, 0x3f317218, v26
	v_mul_f32_e32 v26, v26, v47
	v_mul_f32_e32 v26, 0x3fb8aa3b, v26
	v_exp_f32_e32 v28, v26
	v_lshlrev_b32_e32 v26, 16, v10
	v_lshlrev_b32_e32 v38, 16, v15
	v_and_b32_e32 v39, 0xffff0000, v15
	v_mul_f32_e32 v30, 0x3db504f3, v28
	v_cvt_f32_f16_sdwa v28, v2 dst_sel:DWORD dst_unused:UNUSED_PAD src0_sel:WORD_1
	v_lshlrev_b32_e32 v52, 16, v16
	v_and_b32_e32 v53, 0xffff0000, v16
	v_lshlrev_b32_e32 v60, 16, v17
	v_pk_mul_f32 v[36:37], v[28:29], v[34:35]
	v_and_b32_e32 v61, 0xffff0000, v17
	v_pk_fma_f32 v[36:37], v[26:27], v[32:33], v[36:37] neg_lo:[0,0,1] neg_hi:[0,0,1]
	v_pk_mul_f32 v[26:27], v[26:27], v[28:29]
	v_cvt_f32_f16_sdwa v29, v5 dst_sel:DWORD dst_unused:UNUSED_PAD src0_sel:WORD_1
	v_cvt_f32_f16_sdwa v28, v4 dst_sel:DWORD dst_unused:UNUSED_PAD src0_sel:WORD_1
	v_pk_fma_f32 v[26:27], v[32:33], v[34:35], v[26:27]
	v_cvt_f32_f16_e32 v35, v5
	v_cvt_f32_f16_e32 v34, v4
	v_pk_mul_f32 v[32:33], v[26:27], v[30:31] op_sel_hi:[1,0]
	v_lshlrev_b32_e32 v26, 16, v11
	v_and_b32_e32 v27, 0xffff0000, v11
	v_pk_mul_f32 v[40:41], v[28:29], v[38:39]
	v_pk_mul_f32 v[36:37], v[36:37], v[30:31] op_sel_hi:[1,0]
	v_pk_fma_f32 v[40:41], v[26:27], v[34:35], v[40:41] neg_lo:[0,0,1] neg_hi:[0,0,1]
	v_pk_mul_f32 v[26:27], v[26:27], v[28:29]
	v_cvt_f32_f16_sdwa v29, v7 dst_sel:DWORD dst_unused:UNUSED_PAD src0_sel:WORD_1
	v_cvt_f32_f16_sdwa v28, v6 dst_sel:DWORD dst_unused:UNUSED_PAD src0_sel:WORD_1
	v_pk_fma_f32 v[26:27], v[34:35], v[38:39], v[26:27]
	v_cvt_f32_f16_e32 v39, v7
	v_cvt_f32_f16_e32 v38, v6
	v_pk_mul_f32 v[34:35], v[26:27], v[30:31] op_sel_hi:[1,0]
	v_lshlrev_b32_e32 v26, 16, v12
	v_and_b32_e32 v27, 0xffff0000, v12
	v_pk_mul_f32 v[54:55], v[52:53], v[28:29]
	v_pk_mul_f32 v[40:41], v[40:41], v[30:31] op_sel_hi:[1,0]
	v_pk_fma_f32 v[54:55], v[26:27], v[38:39], v[54:55] neg_lo:[0,0,1] neg_hi:[0,0,1]
	v_pk_mul_f32 v[26:27], v[26:27], v[28:29]
	v_cvt_f32_f16_sdwa v29, v9 dst_sel:DWORD dst_unused:UNUSED_PAD src0_sel:WORD_1
	v_cvt_f32_f16_sdwa v28, v8 dst_sel:DWORD dst_unused:UNUSED_PAD src0_sel:WORD_1
	v_pk_fma_f32 v[26:27], v[52:53], v[38:39], v[26:27]
	v_cvt_f32_f16_e32 v53, v9
	v_cvt_f32_f16_e32 v52, v8
	v_pk_mul_f32 v[38:39], v[26:27], v[30:31] op_sel_hi:[1,0]
	v_lshlrev_b32_e32 v26, 16, v13
	v_and_b32_e32 v27, 0xffff0000, v13
	v_pk_mul_f32 v[62:63], v[60:61], v[28:29]
	v_pk_mul_f32 v[54:55], v[54:55], v[30:31] op_sel_hi:[1,0]
	v_pk_fma_f32 v[62:63], v[26:27], v[52:53], v[62:63] neg_lo:[0,0,1] neg_hi:[0,0,1]
	v_pk_mul_f32 v[26:27], v[26:27], v[28:29]
	v_pk_mul_f32 v[62:63], v[62:63], v[30:31] op_sel_hi:[1,0]
	v_pk_fma_f32 v[26:27], v[60:61], v[52:53], v[26:27]
	s_add_i32 s8, s4, s36
	v_pk_mul_f32 v[30:31], v[26:27], v[30:31] op_sel_hi:[1,0]
	v_cvt_pk_bf16_f32 v26, v36, v37
	v_cvt_pk_bf16_f32 v27, v40, v41
	v_cvt_pk_bf16_f32 v28, v54, v55
	v_cvt_pk_bf16_f32 v29, v62, v63
	s_cmpk_gt_i32 s8, 0x7ff
	s_barrier
	ds_write_b128 v58, v[26:29]
	v_cvt_pk_bf16_f32 v26, v32, v33
	v_cvt_pk_bf16_f32 v27, v34, v35
	v_cvt_pk_bf16_f32 v28, v38, v39
	v_cvt_pk_bf16_f32 v29, v30, v31
	s_cselect_b64 s[2:3], -1, 0
	ds_write_b128 v58, v[26:29] offset:128
	v_add_u32_e32 v26, v56, v44
	s_and_b64 vcc, exec, s[2:3]
	ds_write_b128 v26, v[18:21] offset:18432
	ds_write_b128 v26, v[22:25] offset:18448
	s_cbranch_vccnz .LBB0_382
	s_ashr_i32 s10, s8, 8
	s_ashr_i32 s11, s10, 31
	s_lshl_b64 s[10:11], s[10:11], 12
	s_and_b32 s5, s6, 0xfc0
	s_or_b32 s10, s10, s5
	v_lshl_add_u64 v[2:3], s[10:11], 0, v[42:43]
	v_mov_b64_e32 v[4:5], s[0:1]
	v_mad_u64_u32 v[4:5], s[10:11], v2, s95, v[4:5]
	s_and_b32 s9, s7, 0x180
	v_add_u32_e32 v2, s5, v42
	v_mad_i32_i24 v5, v3, s95, v5
	s_lshl_b32 s44, s9, 1
	v_ashrrev_i32_e32 v3, 31, v2
	v_lshl_add_u64 v[18:19], v[4:5], 0, s[44:45]
	v_lshlrev_b64 v[2:3], 8, v[2:3]
	v_lshlrev_b32_e32 v20, 1, v46
	v_mov_b32_e32 v21, v1
	v_lshl_add_u64 v[6:7], v[48:49], 0, v[2:3]
	v_lshl_add_u64 v[14:15], v[18:19], 0, v[0:1]
	v_lshl_add_u64 v[22:23], v[18:19], 0, v[20:21]
	global_load_dwordx4 v[2:5], v[6:7], off
	s_nop 0
	global_load_dwordx4 v[6:9], v[6:7], off offset:16
	s_nop 0
	global_load_dwordx4 v[10:13], v[14:15], off offset:1024
	s_nop 0
	global_load_dwordx4 v[14:17], v[14:15], off offset:1152
	s_nop 0
	global_load_dwordx4 v[18:21], v[22:23], off offset:2048
	s_nop 0
	global_load_dwordx4 v[22:25], v[22:23], off offset:2064
	s_branch .LBB0_382

.LBB0_567:
	s_or_b64 exec, exec, s[4:5]
	v_add_u32_e32 v86, s12, v144
	s_waitcnt lgkmcnt(0)
	s_barrier
	ds_read_b128 v[82:85], v86 offset:62464
	ds_read_b128 v[86:89], v86 offset:62480
	s_ashr_i32 s4, s6, 8
	s_ashr_i32 s5, s4, 31
	s_lshl_b64 s[4:5], s[4:5], 12
	s_waitcnt lgkmcnt(0)
	v_mov_b32_e32 v100, v83
	v_mov_b32_e32 v101, v84
	v_mov_b32_e32 v83, v85
	v_pk_add_f32 v[82:83], v[100:101], v[82:83]
	v_mov_b32_e32 v84, v88
	v_mov_b32_e32 v85, v86
	v_mov_b32_e32 v86, v89
	v_pk_add_f32 v[84:85], v[84:85], v[86:87]
	v_add_f32_e32 v82, v82, v83
	v_add_f32_e32 v82, v82, v85
	v_add_f32_e32 v82, v84, v82
	v_fmamk_f32 v82, v82, 0x3c000000, v203
	v_mul_f32_e32 v83, 0x4b800000, v82
	v_cmp_gt_f32_e32 vcc, s40, v82
	s_and_b32 s6, s7, 0xfc0
	s_or_b32 s4, s4, s6
	v_cndmask_b32_e32 v82, v82, v83, vcc
	v_rsq_f32_e32 v82, v82
	s_lshl_b32 s44, s14, 8
	s_add_i32 s7, s7, s62
	s_add_i32 s13, s13, s53
	v_mul_f32_e32 v83, 0x45800000, v82
	v_cndmask_b32_e32 v82, v82, v83, vcc
	v_mul_f32_e32 v78, v78, v82
	v_cvt_pk_bf16_f32 v78, v78, s0
	ds_write_b16 v152, v78
	ds_read_b128 v[82:85], v153 offset:62464
	ds_read_b128 v[86:89], v153 offset:62480
	s_mov_b32 s6, s8
	s_waitcnt lgkmcnt(0)
	v_mov_b32_e32 v100, v83
	v_mov_b32_e32 v101, v84
	v_mov_b32_e32 v83, v85
	v_pk_add_f32 v[82:83], v[100:101], v[82:83]
	v_mov_b32_e32 v84, v88
	v_mov_b32_e32 v85, v86
	v_mov_b32_e32 v86, v89
	v_pk_add_f32 v[84:85], v[84:85], v[86:87]
	v_add_f32_e32 v78, v82, v83
	v_add_f32_e32 v78, v78, v85
	v_add_f32_e32 v78, v84, v78
	v_fmamk_f32 v78, v78, 0x3c000000, v203
	v_mul_f32_e32 v82, 0x4b800000, v78
	v_cmp_gt_f32_e32 vcc, s40, v78
	s_nop 1
	v_cndmask_b32_e32 v78, v78, v82, vcc
	v_rsq_f32_e32 v78, v78
	s_nop 0
	v_mul_f32_e32 v82, 0x45800000, v78
	v_cndmask_b32_e32 v78, v78, v82, vcc
	v_mul_f32_e32 v78, v79, v78
	v_cvt_pk_bf16_f32 v78, v78, s0
	ds_write_b16 v154, v78
	ds_read_b128 v[82:85], v155 offset:62464
	ds_read_b128 v[86:89], v155 offset:62480
	s_waitcnt lgkmcnt(0)
	v_mov_b32_e32 v78, v83
	v_mov_b32_e32 v79, v84
	v_mov_b32_e32 v83, v85
	v_pk_add_f32 v[78:79], v[78:79], v[82:83]
	v_mov_b32_e32 v82, v88
	v_mov_b32_e32 v83, v86
	v_mov_b32_e32 v86, v89
	v_pk_add_f32 v[82:83], v[82:83], v[86:87]
	v_add_f32_e32 v78, v78, v79
	v_add_f32_e32 v78, v78, v83
	v_add_f32_e32 v78, v82, v78
	v_fmamk_f32 v78, v78, 0x3c000000, v203
	v_mul_f32_e32 v79, 0x4b800000, v78
	v_cmp_gt_f32_e32 vcc, s40, v78
	s_nop 1
	v_cndmask_b32_e32 v78, v78, v79, vcc
	v_rsq_f32_e32 v78, v78
	s_nop 0
	v_mul_f32_e32 v79, 0x45800000, v78
	v_cndmask_b32_e32 v78, v78, v79, vcc
	v_mul_f32_e32 v78, v80, v78
	v_cvt_pk_bf16_f32 v78, v78, s0
	ds_write_b16 v154, v78 offset:272
	ds_read_b128 v[82:85], v156 offset:62464
	ds_read_b128 v[86:89], v156 offset:62480
	s_waitcnt lgkmcnt(0)
	v_mov_b32_e32 v78, v83
	v_mov_b32_e32 v79, v84
	v_mov_b32_e32 v83, v85
	v_pk_add_f32 v[78:79], v[78:79], v[82:83]
	v_mov_b32_e32 v82, v88
	v_mov_b32_e32 v83, v86
	v_mov_b32_e32 v86, v89
	v_pk_add_f32 v[82:83], v[82:83], v[86:87]
	v_add_f32_e32 v78, v78, v79
	v_add_f32_e32 v78, v78, v83
	v_add_f32_e32 v78, v82, v78
	v_fmamk_f32 v78, v78, 0x3c000000, v203
	v_mul_f32_e32 v79, 0x4b800000, v78
	v_cmp_gt_f32_e32 vcc, s40, v78
	v_add_u32_e32 v82, s12, v145
	s_nop 0
	v_cndmask_b32_e32 v78, v78, v79, vcc
	v_rsq_f32_e32 v78, v78
	s_nop 0
	v_mul_f32_e32 v79, 0x45800000, v78
	v_cndmask_b32_e32 v78, v78, v79, vcc
	v_mul_f32_e32 v78, v81, v78
	v_cvt_pk_bf16_f32 v78, v78, s0
	ds_write_b16 v154, v78 offset:544
	ds_read_b128 v[78:81], v82 offset:62464
	ds_read_b128 v[82:85], v82 offset:62480
	s_waitcnt lgkmcnt(0)
	v_mov_b32_e32 v86, v79
	v_mov_b32_e32 v87, v80
	v_mov_b32_e32 v79, v81
	v_pk_add_f32 v[78:79], v[86:87], v[78:79]
	v_mov_b32_e32 v80, v84
	v_mov_b32_e32 v81, v82
	v_mov_b32_e32 v82, v85
	v_pk_add_f32 v[80:81], v[80:81], v[82:83]
	v_add_f32_e32 v78, v78, v79
	v_add_f32_e32 v78, v78, v81
	v_add_f32_e32 v78, v80, v78
	v_fmamk_f32 v78, v78, 0x3c000000, v203
	v_mul_f32_e32 v79, 0x4b800000, v78
	v_cmp_gt_f32_e32 vcc, s40, v78
	s_nop 1
	v_cndmask_b32_e32 v78, v78, v79, vcc
	v_rsq_f32_e32 v78, v78
	s_nop 0
	v_mul_f32_e32 v79, 0x45800000, v78
	v_cndmask_b32_e32 v78, v78, v79, vcc
	v_mul_f32_e32 v74, v74, v78
	v_cvt_pk_bf16_f32 v74, v74, s0
	ds_write_b16 v154, v74 offset:4080
	ds_read_b128 v[78:81], v157 offset:62464
	ds_read_b128 v[82:85], v157 offset:62480
	s_waitcnt lgkmcnt(0)
	v_mov_b32_e32 v86, v79
	v_mov_b32_e32 v87, v80
	v_mov_b32_e32 v79, v81
	v_pk_add_f32 v[78:79], v[86:87], v[78:79]
	v_mov_b32_e32 v80, v84
	v_mov_b32_e32 v81, v82
	v_mov_b32_e32 v82, v85
	v_pk_add_f32 v[80:81], v[80:81], v[82:83]
	v_add_f32_e32 v74, v78, v79
	v_add_f32_e32 v74, v74, v81
	v_add_f32_e32 v74, v80, v74
	v_fmamk_f32 v74, v74, 0x3c000000, v203
	v_mul_f32_e32 v78, 0x4b800000, v74
	v_cmp_gt_f32_e32 vcc, s40, v74
	s_nop 1
	v_cndmask_b32_e32 v74, v74, v78, vcc
	v_rsq_f32_e32 v74, v74
	s_nop 0
	v_mul_f32_e32 v78, 0x45800000, v74
	v_cndmask_b32_e32 v74, v74, v78, vcc
	v_mul_f32_e32 v74, v75, v74
	v_cvt_pk_bf16_f32 v74, v74, s0
	ds_write_b16 v154, v74 offset:4352
	ds_read_b128 v[78:81], v158 offset:62464
	ds_read_b128 v[82:85], v158 offset:62480
	s_waitcnt lgkmcnt(0)
	v_mov_b32_e32 v74, v79
	v_mov_b32_e32 v75, v80
	v_mov_b32_e32 v79, v81
	v_pk_add_f32 v[74:75], v[74:75], v[78:79]
	v_mov_b32_e32 v78, v84
	v_mov_b32_e32 v79, v82
	v_mov_b32_e32 v82, v85
	v_pk_add_f32 v[78:79], v[78:79], v[82:83]
	v_add_f32_e32 v74, v74, v75
	v_add_f32_e32 v74, v74, v79
	v_add_f32_e32 v74, v78, v74
	v_fmamk_f32 v74, v74, 0x3c000000, v203
	v_mul_f32_e32 v75, 0x4b800000, v74
	v_cmp_gt_f32_e32 vcc, s40, v74
	s_nop 1
	v_cndmask_b32_e32 v74, v74, v75, vcc
	v_rsq_f32_e32 v74, v74
	s_nop 0
	v_mul_f32_e32 v75, 0x45800000, v74
	v_cndmask_b32_e32 v74, v74, v75, vcc
	v_mul_f32_e32 v74, v76, v74
	v_cvt_pk_bf16_f32 v74, v74, s0
	ds_write_b16 v154, v74 offset:4624
	ds_read_b128 v[78:81], v159 offset:62464
	ds_read_b128 v[82:85], v159 offset:62480
	s_waitcnt lgkmcnt(0)
	v_mov_b32_e32 v74, v79
	v_mov_b32_e32 v75, v80
	v_mov_b32_e32 v79, v81
	v_pk_add_f32 v[74:75], v[74:75], v[78:79]
	v_mov_b32_e32 v78, v84
	v_mov_b32_e32 v79, v82
	v_mov_b32_e32 v82, v85
	v_pk_add_f32 v[78:79], v[78:79], v[82:83]
	v_add_f32_e32 v74, v74, v75
	v_add_f32_e32 v74, v74, v79
	v_add_f32_e32 v74, v78, v74
	v_fmamk_f32 v74, v74, 0x3c000000, v203
	v_mul_f32_e32 v75, 0x4b800000, v74
	v_cmp_gt_f32_e32 vcc, s40, v74
	v_add_u32_e32 v78, s12, v146
	s_nop 0
	v_cndmask_b32_e32 v74, v74, v75, vcc
	v_rsq_f32_e32 v74, v74
	s_nop 0
	v_mul_f32_e32 v75, 0x45800000, v74
	v_cndmask_b32_e32 v74, v74, v75, vcc
	v_mul_f32_e32 v74, v77, v74
	v_cvt_pk_bf16_f32 v74, v74, s0
	ds_write_b16 v154, v74 offset:4896
	ds_read_b128 v[74:77], v78 offset:62464
	ds_read_b128 v[78:81], v78 offset:62480
	s_waitcnt lgkmcnt(0)
	v_mov_b32_e32 v82, v75
	v_mov_b32_e32 v83, v76
	v_mov_b32_e32 v75, v77
	v_pk_add_f32 v[74:75], v[82:83], v[74:75]
	v_mov_b32_e32 v76, v80
	v_mov_b32_e32 v77, v78
	v_mov_b32_e32 v78, v81
	v_pk_add_f32 v[76:77], v[76:77], v[78:79]
	v_add_f32_e32 v74, v74, v75
	v_add_f32_e32 v74, v74, v77
	v_add_f32_e32 v74, v76, v74
	v_fmamk_f32 v74, v74, 0x3c000000, v203
	v_mul_f32_e32 v75, 0x4b800000, v74
	v_cmp_gt_f32_e32 vcc, s40, v74
	s_nop 1
	v_cndmask_b32_e32 v74, v74, v75, vcc
	v_rsq_f32_e32 v74, v74
	s_nop 0
	v_mul_f32_e32 v75, 0x45800000, v74
	v_cndmask_b32_e32 v74, v74, v75, vcc
	v_mul_f32_e32 v70, v70, v74
	v_cvt_pk_bf16_f32 v70, v70, s0
	ds_write_b16 v154, v70 offset:8432
	ds_read_b128 v[74:77], v160 offset:62464
	ds_read_b128 v[78:81], v160 offset:62480
	s_waitcnt lgkmcnt(0)
	v_mov_b32_e32 v82, v75
	v_mov_b32_e32 v83, v76
	v_mov_b32_e32 v75, v77
	v_pk_add_f32 v[74:75], v[82:83], v[74:75]
	v_mov_b32_e32 v76, v80
	v_mov_b32_e32 v77, v78
	v_mov_b32_e32 v78, v81
	v_pk_add_f32 v[76:77], v[76:77], v[78:79]
	v_add_f32_e32 v70, v74, v75
	v_add_f32_e32 v70, v70, v77
	v_add_f32_e32 v70, v76, v70
	v_fmamk_f32 v70, v70, 0x3c000000, v203
	v_mul_f32_e32 v74, 0x4b800000, v70
	v_cmp_gt_f32_e32 vcc, s40, v70
	s_nop 1
	v_cndmask_b32_e32 v70, v70, v74, vcc
	v_rsq_f32_e32 v70, v70
	s_nop 0
	v_mul_f32_e32 v74, 0x45800000, v70
	v_cndmask_b32_e32 v70, v70, v74, vcc
	v_mul_f32_e32 v70, v71, v70
	v_cvt_pk_bf16_f32 v70, v70, s0
	ds_write_b16 v154, v70 offset:8704
	ds_read_b128 v[74:77], v161 offset:62464
	ds_read_b128 v[78:81], v161 offset:62480
	s_waitcnt lgkmcnt(0)
	v_mov_b32_e32 v70, v75
	v_mov_b32_e32 v71, v76
	v_mov_b32_e32 v75, v77
	v_pk_add_f32 v[70:71], v[70:71], v[74:75]
	v_mov_b32_e32 v74, v80
	v_mov_b32_e32 v75, v78
	v_mov_b32_e32 v78, v81
	v_pk_add_f32 v[74:75], v[74:75], v[78:79]
	v_add_f32_e32 v70, v70, v71
	v_add_f32_e32 v70, v70, v75
	v_add_f32_e32 v70, v74, v70
	v_fmamk_f32 v70, v70, 0x3c000000, v203
	v_mul_f32_e32 v71, 0x4b800000, v70
	v_cmp_gt_f32_e32 vcc, s40, v70
	s_nop 1
	v_cndmask_b32_e32 v70, v70, v71, vcc
	v_rsq_f32_e32 v70, v70
	s_nop 0
	v_mul_f32_e32 v71, 0x45800000, v70
	v_cndmask_b32_e32 v70, v70, v71, vcc
	v_mul_f32_e32 v70, v72, v70
	v_cvt_pk_bf16_f32 v70, v70, s0
	ds_write_b16 v154, v70 offset:8976
	ds_read_b128 v[74:77], v162 offset:62464
	ds_read_b128 v[78:81], v162 offset:62480
	s_waitcnt lgkmcnt(0)
	v_mov_b32_e32 v70, v75
	v_mov_b32_e32 v71, v76
	v_mov_b32_e32 v75, v77
	v_pk_add_f32 v[70:71], v[70:71], v[74:75]
	v_mov_b32_e32 v74, v80
	v_mov_b32_e32 v75, v78
	v_mov_b32_e32 v78, v81
	v_pk_add_f32 v[74:75], v[74:75], v[78:79]
	v_add_f32_e32 v70, v70, v71
	v_add_f32_e32 v70, v70, v75
	v_add_f32_e32 v70, v74, v70
	v_fmamk_f32 v70, v70, 0x3c000000, v203
	v_mul_f32_e32 v71, 0x4b800000, v70
	v_cmp_gt_f32_e32 vcc, s40, v70
	v_add_u32_e32 v74, s12, v147
	v_lshlrev_b32_e32 v80, 16, v34
	v_cndmask_b32_e32 v70, v70, v71, vcc
	v_rsq_f32_e32 v70, v70
	v_and_b32_e32 v81, 0xffff0000, v34
	v_mul_f32_e32 v34, 0xbfb8aa3b, v80
	v_exp_f32_e32 v34, v34
	v_mul_f32_e32 v71, 0x45800000, v70
	v_cndmask_b32_e32 v70, v70, v71, vcc
	v_mul_f32_e32 v70, v73, v70
	v_cvt_pk_bf16_f32 v70, v70, s0
	ds_write_b16 v154, v70 offset:9248
	ds_read_b128 v[70:73], v74 offset:62464
	ds_read_b128 v[74:77], v74 offset:62480
	v_add_f32_e32 v34, 1.0, v34
	s_waitcnt lgkmcnt(0)
	v_mov_b32_e32 v78, v71
	v_mov_b32_e32 v79, v72
	v_mov_b32_e32 v71, v73
	v_pk_add_f32 v[70:71], v[78:79], v[70:71]
	v_mov_b32_e32 v72, v76
	v_mov_b32_e32 v73, v74
	v_mov_b32_e32 v74, v77
	v_pk_add_f32 v[72:73], v[72:73], v[74:75]
	v_add_f32_e32 v70, v70, v71
	v_add_f32_e32 v70, v70, v73
	v_add_f32_e32 v70, v72, v70
	v_fmamk_f32 v70, v70, 0x3c000000, v203
	v_mul_f32_e32 v71, 0x4b800000, v70
	v_cmp_gt_f32_e32 vcc, s40, v70
	s_nop 1
	v_cndmask_b32_e32 v70, v70, v71, vcc
	v_rsq_f32_e32 v70, v70
	s_nop 0
	v_mul_f32_e32 v71, 0x45800000, v70
	v_cndmask_b32_e32 v70, v70, v71, vcc
	v_mul_f32_e32 v66, v66, v70
	v_cvt_pk_bf16_f32 v66, v66, s0
	ds_write_b16 v154, v66 offset:12784
	ds_read_b128 v[70:73], v163 offset:62464
	ds_read_b128 v[74:77], v163 offset:62480
	s_waitcnt lgkmcnt(0)
	v_mov_b32_e32 v78, v71
	v_mov_b32_e32 v79, v72
	v_mov_b32_e32 v71, v73
	v_pk_add_f32 v[70:71], v[78:79], v[70:71]
	v_mov_b32_e32 v72, v76
	v_mov_b32_e32 v73, v74
	v_mov_b32_e32 v74, v77
	v_pk_add_f32 v[72:73], v[72:73], v[74:75]
	v_add_f32_e32 v66, v70, v71
	v_add_f32_e32 v66, v66, v73
	v_add_f32_e32 v66, v72, v66
	v_fmamk_f32 v66, v66, 0x3c000000, v203
	v_mul_f32_e32 v70, 0x4b800000, v66
	v_cmp_gt_f32_e32 vcc, s40, v66
	s_nop 1
	v_cndmask_b32_e32 v66, v66, v70, vcc
	v_rsq_f32_e32 v66, v66
	s_nop 0
	v_mul_f32_e32 v70, 0x45800000, v66
	v_cndmask_b32_e32 v66, v66, v70, vcc
	v_mul_f32_e32 v66, v67, v66
	v_cvt_pk_bf16_f32 v66, v66, s0
	ds_write_b16 v154, v66 offset:13056
	ds_read_b128 v[70:73], v164 offset:62464
	ds_read_b128 v[74:77], v164 offset:62480
	s_waitcnt lgkmcnt(0)
	v_mov_b32_e32 v66, v71
	v_mov_b32_e32 v67, v72
	v_mov_b32_e32 v71, v73
	v_pk_add_f32 v[66:67], v[66:67], v[70:71]
	v_mov_b32_e32 v70, v76
	v_mov_b32_e32 v71, v74
	v_mov_b32_e32 v74, v77
	v_pk_add_f32 v[70:71], v[70:71], v[74:75]
	v_add_f32_e32 v66, v66, v67
	v_add_f32_e32 v66, v66, v71
	v_add_f32_e32 v66, v70, v66
	v_fmamk_f32 v66, v66, 0x3c000000, v203
	v_mul_f32_e32 v67, 0x4b800000, v66
	v_cmp_gt_f32_e32 vcc, s40, v66
	s_nop 1
	v_cndmask_b32_e32 v66, v66, v67, vcc
	v_rsq_f32_e32 v66, v66
	s_nop 0
	v_mul_f32_e32 v67, 0x45800000, v66
	v_cndmask_b32_e32 v66, v66, v67, vcc
	v_mul_f32_e32 v66, v68, v66
	v_cvt_pk_bf16_f32 v66, v66, s0
	ds_write_b16 v154, v66 offset:13328
	v_add_u32_e32 v66, s12, v148
	ds_read_b128 v[70:73], v66 offset:62464
	ds_read_b128 v[74:77], v66 offset:62480
	s_waitcnt lgkmcnt(0)
	v_mov_b32_e32 v66, v71
	v_mov_b32_e32 v67, v72
	v_mov_b32_e32 v71, v73
	v_pk_add_f32 v[66:67], v[66:67], v[70:71]
	v_mov_b32_e32 v70, v76
	v_mov_b32_e32 v71, v74
	v_mov_b32_e32 v74, v77
	v_pk_add_f32 v[70:71], v[70:71], v[74:75]
	v_add_f32_e32 v66, v66, v67
	v_add_f32_e32 v66, v66, v71
	v_add_f32_e32 v66, v70, v66
	v_lshlrev_b32_e32 v76, 16, v38
	v_fmamk_f32 v66, v66, 0x3c000000, v203
	v_and_b32_e32 v77, 0xffff0000, v38
	v_mul_f32_e32 v38, 0xbfb8aa3b, v76
	v_mul_f32_e32 v67, 0x4b800000, v66
	v_cmp_gt_f32_e32 vcc, s40, v66
	v_exp_f32_e32 v38, v38
	v_mul_f32_e32 v75, 0xbfb8aa3b, v77
	v_cndmask_b32_e32 v66, v66, v67, vcc
	v_exp_f32_e32 v79, v75
	v_rsq_f32_e32 v66, v66
	v_add_f32_e32 v38, 1.0, v38
	v_rcp_f32_e32 v78, v38
	v_add_f32_e32 v38, 1.0, v79
	v_mul_f32_e32 v67, 0x45800000, v66
	v_rcp_f32_e32 v79, v38
	v_mul_f32_e32 v38, 0xbfb8aa3b, v81
	v_cndmask_b32_e32 v66, v66, v67, vcc
	v_exp_f32_e32 v38, v38
	v_mul_f32_e32 v66, v69, v66
	v_cvt_pk_bf16_f32 v66, v66, s0
	ds_write_b16 v154, v66 offset:13600
	s_waitcnt lgkmcnt(0)
	s_barrier
	ds_read_b128 v[66:69], v111
	ds_read_b128 v[70:73], v111 offset:16
	v_pk_mul_f32 v[76:77], v[78:79], v[76:77]
	v_rcp_f32_e32 v78, v34
	v_add_f32_e32 v34, 1.0, v38
	v_rcp_f32_e32 v79, v34
	s_waitcnt lgkmcnt(0)
	v_lshlrev_b32_e32 v74, 16, v66
	v_and_b32_e32 v75, 0xffff0000, v66
	v_pk_mul_f32 v[74:75], v[76:77], v[74:75]
	v_lshlrev_b32_e32 v76, 16, v70
	v_and_b32_e32 v77, 0xffff0000, v70
	v_pk_mul_f32 v[78:79], v[78:79], v[80:81]
	v_lshlrev_b32_e32 v38, 16, v67
	v_pk_mul_f32 v[76:77], v[78:79], v[76:77]
	v_lshlrev_b32_e32 v78, 16, v39
	v_and_b32_e32 v79, 0xffff0000, v39
	v_mul_f32_e32 v34, 0xbfb8aa3b, v78
	v_exp_f32_e32 v34, v34
	v_mul_f32_e32 v39, 0xbfb8aa3b, v79
	v_exp_f32_e32 v70, v39
	v_and_b32_e32 v39, 0xffff0000, v67
	v_add_f32_e32 v34, 1.0, v34
	v_rcp_f32_e32 v66, v34
	v_add_f32_e32 v34, 1.0, v70
	v_rcp_f32_e32 v67, v34
	v_lshlrev_b32_e32 v34, 16, v35
	v_and_b32_e32 v35, 0xffff0000, v35
	v_mul_f32_e32 v70, 0xbfb8aa3b, v34
	v_exp_f32_e32 v70, v70
	v_mul_f32_e32 v80, 0xbfb8aa3b, v35
	v_exp_f32_e32 v80, v80
	v_pk_mul_f32 v[66:67], v[66:67], v[78:79]
	v_add_f32_e32 v70, 1.0, v70
	v_rcp_f32_e32 v78, v70
	v_add_f32_e32 v70, 1.0, v80
	v_rcp_f32_e32 v79, v70
	v_pk_mul_f32 v[38:39], v[66:67], v[38:39]
	v_lshlrev_b32_e32 v66, 16, v71
	v_and_b32_e32 v67, 0xffff0000, v71
	v_pk_mul_f32 v[34:35], v[78:79], v[34:35]
	v_lshlrev_b32_e32 v70, 16, v40
	v_pk_mul_f32 v[66:67], v[34:35], v[66:67]
	v_and_b32_e32 v71, 0xffff0000, v40
	v_mul_f32_e32 v35, 0xbfb8aa3b, v70
	v_exp_f32_e32 v40, v35
	v_mul_f32_e32 v35, 0xbfb8aa3b, v71
	v_exp_f32_e32 v79, v35
	v_lshlrev_b32_e32 v80, 16, v36
	v_add_f32_e32 v40, 1.0, v40
	v_rcp_f32_e32 v78, v40
	v_add_f32_e32 v40, 1.0, v79
	v_and_b32_e32 v81, 0xffff0000, v36
	v_mul_f32_e32 v36, 0xbfb8aa3b, v80
	v_rcp_f32_e32 v79, v40
	v_exp_f32_e32 v36, v36
	v_mul_f32_e32 v40, 0xbfb8aa3b, v81
	v_exp_f32_e32 v40, v40
	v_pk_mul_f32 v[70:71], v[78:79], v[70:71]
	v_add_f32_e32 v36, 1.0, v36
	v_rcp_f32_e32 v78, v36
	v_add_f32_e32 v36, 1.0, v40
	v_rcp_f32_e32 v79, v36
	v_lshlrev_b32_e32 v34, 16, v68
	v_and_b32_e32 v35, 0xffff0000, v68
	v_pk_mul_f32 v[70:71], v[70:71], v[34:35]
	v_lshlrev_b32_e32 v34, 16, v72
	v_and_b32_e32 v35, 0xffff0000, v72
	v_pk_mul_f32 v[78:79], v[78:79], v[80:81]
	v_lshlrev_b32_e32 v40, 16, v41
	v_pk_mul_f32 v[78:79], v[78:79], v[34:35]
	v_and_b32_e32 v41, 0xffff0000, v41
	v_mul_f32_e32 v35, 0xbfb8aa3b, v40
	v_exp_f32_e32 v36, v35
	v_mul_f32_e32 v35, 0xbfb8aa3b, v41
	v_exp_f32_e32 v72, v35
	v_lshlrev_b32_e32 v34, 16, v69
	v_add_f32_e32 v36, 1.0, v36
	v_rcp_f32_e32 v68, v36
	v_add_f32_e32 v36, 1.0, v72
	v_and_b32_e32 v35, 0xffff0000, v69
	v_rcp_f32_e32 v69, v36
	v_lshlrev_b32_e32 v36, 16, v37
	v_and_b32_e32 v37, 0xffff0000, v37
	v_mul_f32_e32 v72, 0xbfb8aa3b, v36
	v_mul_f32_e32 v80, 0xbfb8aa3b, v37
	v_exp_f32_e32 v72, v72
	v_exp_f32_e32 v80, v80
	v_pk_mul_f32 v[40:41], v[68:69], v[40:41]
	s_andn2_b64 vcc, exec, s[10:11]
	v_add_f32_e32 v68, 1.0, v72
	v_add_f32_e32 v69, 1.0, v80
	v_rcp_f32_e32 v68, v68
	v_rcp_f32_e32 v69, v69
	v_pk_mul_f32 v[40:41], v[40:41], v[34:35]
	v_lshlrev_b32_e32 v34, 16, v73
	v_and_b32_e32 v35, 0xffff0000, v73
	v_pk_mul_f32 v[36:37], v[68:69], v[36:37]
	s_nop 0
	v_pk_mul_f32 v[68:69], v[36:37], v[34:35]
	v_lshl_add_u64 v[34:35], s[4:5], 0, v[90:91]
	v_mov_b64_e32 v[36:37], s[0:1]
	v_mad_u64_u32 v[36:37], s[4:5], v34, s95, v[36:37]
	v_mad_i32_i24 v37, v35, s95, v37
	v_lshl_add_u64 v[34:35], v[36:37], 0, s[44:45]
	v_lshl_add_u64 v[72:73], v[34:35], 0, v[0:1]
	v_cvt_pk_bf16_f32 v34, v74, v75
	v_cvt_pk_bf16_f32 v35, v38, v39
	v_cvt_pk_bf16_f32 v36, v70, v71
	v_cvt_pk_bf16_f32 v37, v40, v41
	s_waitcnt vmcnt(0)
	flat_store_dwordx4 v[72:73], v[34:37]
	v_mov_b64_e32 v[38:39], v[46:47]
	v_mov_b64_e32 v[40:41], v[48:49]
	v_cvt_pk_bf16_f32 v34, v76, v77
	v_cvt_pk_bf16_f32 v35, v66, v67
	v_cvt_pk_bf16_f32 v36, v78, v79
	v_cvt_pk_bf16_f32 v37, v68, v69
	flat_store_dwordx4 v[72:73], v[34:37] offset:16
	v_mov_b64_e32 v[80:81], v[52:53]
	v_mov_b64_e32 v[76:77], v[56:57]
	v_mov_b64_e32 v[72:73], v[60:61]
	v_mov_b64_e32 v[68:69], v[64:65]
	v_mov_b64_e32 v[34:35], v[42:43]
	v_mov_b64_e32 v[78:79], v[50:51]
	v_mov_b64_e32 v[74:75], v[54:55]
	v_mov_b64_e32 v[70:71], v[58:59]
	v_mov_b64_e32 v[66:67], v[62:63]
	v_mov_b64_e32 v[36:37], v[44:45]
	s_cbranch_vccz .LBB0_602

.LBB0_963:
	s_or_b64 exec, exec, s[68:69]
	s_mov_b32 s0, s45
	s_waitcnt lgkmcnt(0)
	s_barrier
	s_add_i32 s0, s0, 0x200e8
	v_mov_b32_e32 v0, s0
	ds_read_b64 v[2:3], v0
	s_mov_b32 s2, 0
	s_add_i32 s2, s2, 0x200e8
	v_mov_b32_e32 v0, s2
	s_mov_b32 s2, 0
	s_waitcnt lgkmcnt(0)
	v_readfirstlane_b32 s1, v3
	v_readfirstlane_b32 s0, v2
	ds_read_b64 v[2:3], v0
	s_add_i32 s2, s2, 0x200e8
	v_mov_b32_e32 v0, s2
	s_mov_b32 s2, 0
	ds_read_b64 v[4:5], v0
	s_add_i32 s2, s2, 0x200e8
	v_mov_b32_e32 v0, s2
	s_mov_b32 s2, 0
	ds_read_b64 v[6:7], v0
	s_add_i32 s2, s2, 0x200e8
	v_mov_b32_e32 v0, s2
	s_mov_b32 s2, 0
	s_waitcnt lgkmcnt(0)
	v_readfirstlane_b32 s5, v3
	v_readfirstlane_b32 s4, v2
	ds_read_b64 v[2:3], v0
	s_add_i32 s2, s2, 0x20078
	v_mov_b32_e32 v0, s2
	s_mov_b32 s2, 0
	v_readfirstlane_b32 s7, v5
	v_readfirstlane_b32 s6, v4
	ds_read_b64 v[4:5], v0
	s_add_i32 s2, s2, 0x20080
	v_mov_b32_e32 v0, s2
	v_readfirstlane_b32 s9, v7
	v_readfirstlane_b32 s8, v6
	ds_read_b64 v[6:7], v0
	v_readlane_b32 s14, v252, 0
	v_mov_b32_e32 v0, v200
	s_mov_b32 s2, 0x200000
	v_lshl_add_u32 v40, s14, 9, v0
	s_waitcnt lgkmcnt(0)
	v_readfirstlane_b32 s11, v3
	v_readfirstlane_b32 s10, v2
	v_readfirstlane_b32 s13, v5
	v_readfirstlane_b32 s12, v4
	v_readfirstlane_b32 s15, v7
	v_readfirstlane_b32 s16, v6
	v_cmp_gt_i32_e32 vcc, s2, v40
	s_and_saveexec_b64 s[2:3], vcc
	s_cbranch_execz .LBB0_966
	s_add_u32 s4, s4, 0x4bf0000
	s_addc_u32 s5, s5, 0
	s_add_u32 s6, s6, 0x2bf0000
	s_addc_u32 s7, s7, 0
	s_add_u32 s8, s8, 0x210000
	s_addc_u32 s9, s9, 0
	s_add_u32 s10, s10, 0x110000
	s_addc_u32 s11, s11, 0
	s_lshl_b64 s[18:19], s[70:71], 2
	s_add_u32 s12, s12, s18
	s_addc_u32 s13, s13, s19
	s_add_u32 s18, s16, s18
	v_lshlrev_b32_e32 v0, 3, v0
	s_addc_u32 s19, s15, s19
	v_lshl_add_u32 v41, s14, 12, v0
	s_mov_b64 s[20:21], 0
	v_mov_b32_e32 v61, 0
.LBB0_965:
	v_ashrrev_i32_e32 v2, 6, v40
	v_and_b32_e32 v10, 0x1f8, v41
	v_mov_b64_e32 v[4:5], s[0:1]
	v_ashrrev_i32_e32 v3, 31, v2
	v_mad_i64_i32 v[4:5], s[14:15], v2, s95, v[4:5]
	v_lshlrev_b32_e32 v0, 1, v10
	v_bfe_u32 v11, v41, 6, 3
	v_lshl_add_u64 v[4:5], v[4:5], 0, v[0:1]
	v_lshlrev_b64 v[6:7], 10, v[2:3]
	v_lshlrev_b64 v[2:3], 3, v[2:3]
	v_add_co_u32_e32 v38, vcc, 0x8bf0000, v4
	v_lshl_add_u64 v[8:9], s[4:5], 0, v[6:7]
	v_or_b32_e32 v2, v2, v11
	v_addc_co_u32_e32 v39, vcc, 0, v5, vcc
	v_lshl_add_u64 v[4:5], v[8:9], 0, v[0:1]
	v_lshlrev_b64 v[8:9], 5, v[2:3]
	v_lshl_add_u64 v[6:7], s[6:7], 0, v[6:7]
	v_lshl_add_u64 v[42:43], v[2:3], 2, s[10:11]
	v_lshl_add_u64 v[2:3], s[8:9], 0, v[8:9]
	v_lshl_add_u64 v[6:7], v[6:7], 0, v[0:1]
	flat_load_dwordx4 v[30:33], v[38:39] offset:1024
	flat_load_dwordx4 v[22:25], v[4:5]
	flat_load_dwordx4 v[18:21], v[6:7]
	flat_load_dwordx4 v[34:37], v[2:3]
	flat_load_dwordx4 v[26:29], v[2:3] offset:16
	v_lshlrev_b32_e32 v0, 2, v10
	v_lshl_add_u64 v[4:5], s[12:13], 0, v[0:1]
	v_lshl_add_u64 v[14:15], s[18:19], 0, v[0:1]
	flat_load_dwordx4 v[6:9], v[14:15]
	flat_load_dwordx4 v[10:13], v[4:5]
	s_nop 0
	flat_load_dwordx4 v[2:5], v[4:5] offset:16
	s_nop 0
	flat_load_dwordx4 v[14:17], v[14:15] offset:16
	s_nop 0
	flat_load_dword v0, v[42:43]
	s_mov_b32 s22, 0x3c800000
	v_add_u32_e32 v40, s38, v40
	s_mov_b32 s14, 0x1fffff
	v_cmp_lt_i32_e32 vcc, s14, v40
	s_or_b64 s[20:21], vcc, s[20:21]
	v_add_u32_e32 v41, s54, v41
	v_ashrrev_i32_e32 v62, 6, v40
	v_and_b32_e32 v70, 0x1f8, v41
	v_mov_b64_e32 v[64:65], s[0:1]
	v_ashrrev_i32_e32 v63, 31, v62
	v_mad_i64_i32 v[64:65], s[14:15], v62, s95, v[64:65]
	v_lshlrev_b32_e32 v60, 1, v70
	v_bfe_u32 v71, v41, 6, 3
	v_lshl_add_u64 v[64:65], v[64:65], 0, v[60:61]
	v_lshlrev_b64 v[66:67], 10, v[62:63]
	v_lshlrev_b64 v[62:63], 3, v[62:63]
	v_add_co_u32_e32 v98, vcc, 0x8bf0000, v64
	v_lshl_add_u64 v[68:69], s[4:5], 0, v[66:67]
	v_or_b32_e32 v62, v62, v71
	v_addc_co_u32_e32 v99, vcc, 0, v65, vcc
	v_lshl_add_u64 v[64:65], v[68:69], 0, v[60:61]
	v_lshlrev_b64 v[68:69], 5, v[62:63]
	v_lshl_add_u64 v[66:67], s[6:7], 0, v[66:67]
	v_lshl_add_u64 v[102:103], v[62:63], 2, s[10:11]
	v_lshl_add_u64 v[62:63], s[8:9], 0, v[68:69]
	v_lshl_add_u64 v[66:67], v[66:67], 0, v[60:61]
	flat_load_dwordx4 v[90:93], v[98:99] offset:1024
	flat_load_dwordx4 v[82:85], v[64:65]
	flat_load_dwordx4 v[78:81], v[66:67]
	flat_load_dwordx4 v[94:97], v[62:63]
	flat_load_dwordx4 v[86:89], v[62:63] offset:16
	v_lshlrev_b32_e32 v60, 2, v70
	v_lshl_add_u64 v[64:65], s[12:13], 0, v[60:61]
	v_lshl_add_u64 v[74:75], s[18:19], 0, v[60:61]
	flat_load_dwordx4 v[66:69], v[74:75]
	flat_load_dwordx4 v[70:73], v[64:65]
	s_nop 0
	flat_load_dwordx4 v[62:65], v[64:65] offset:16
	s_nop 0
	flat_load_dwordx4 v[74:77], v[74:75] offset:16
	s_nop 0
	flat_load_dword v60, v[102:103]
	s_mov_b32 s22, 0x3c800000
	v_add_u32_e32 v40, s38, v40
	s_mov_b32 s14, 0x1fffff
	v_cmp_lt_i32_e32 vcc, s14, v40
	s_or_b64 s[20:21], vcc, s[20:21]
	v_add_u32_e32 v41, s54, v41
	s_waitcnt vmcnt(0) lgkmcnt(0)
	v_lshlrev_b32_e32 v42, 16, v30
	v_and_b32_e32 v43, 0xffff0000, v30
	v_pk_add_f32 v[34:35], v[34:35], v[36:37]
	v_lshlrev_b32_e32 v30, 16, v31
	v_pk_add_f32 v[26:27], v[34:35], v[26:27]
	v_and_b32_e32 v31, 0xffff0000, v31
	v_pk_add_f32 v[26:27], v[28:29], v[26:27]
	v_lshlrev_b32_e32 v48, 16, v32
	v_pk_mul_f32 v[26:27], v[26:27], s[22:23] op_sel_hi:[1,0]
	v_and_b32_e32 v49, 0xffff0000, v32
	v_lshlrev_b32_e32 v32, 16, v33
	v_and_b32_e32 v33, 0xffff0000, v33
	v_fma_f32 v36, -v26, v26, v27
	v_pk_add_f32 v[28:29], v[42:43], v[26:27] op_sel_hi:[1,0] neg_lo:[0,1] neg_hi:[0,1]
	v_pk_add_f32 v[30:31], v[30:31], v[26:27] op_sel_hi:[1,0] neg_lo:[0,1] neg_hi:[0,1]
	v_pk_add_f32 v[34:35], v[48:49], v[26:27] op_sel_hi:[1,0] neg_lo:[0,1] neg_hi:[0,1]
	v_pk_add_f32 v[26:27], v[32:33], v[26:27] op_sel_hi:[1,0] neg_lo:[0,1] neg_hi:[0,1]
	v_max_f32_e32 v32, 0, v36
	v_add_f32_e32 v32, 0x3a27c5ac, v32
	v_mul_f32_e32 v33, 0x4b800000, v32
	v_cmp_gt_f32_e32 vcc, s40, v32
	v_lshlrev_b32_e32 v46, 16, v18
	v_and_b32_e32 v47, 0xffff0000, v18
	v_cndmask_b32_e32 v32, v32, v33, vcc
	v_rsq_f32_e32 v32, v32
	v_lshlrev_b32_e32 v18, 16, v19
	v_and_b32_e32 v19, 0xffff0000, v19
	v_lshlrev_b32_e32 v52, 16, v20
	v_mul_f32_e32 v33, 0x45800000, v32
	v_cndmask_b32_e32 v32, v32, v33, vcc
	v_pk_mul_f32 v[28:29], v[28:29], v[32:33] op_sel_hi:[1,0]
	v_pk_mul_f32 v[30:31], v[30:31], v[32:33] op_sel_hi:[1,0]
	v_pk_mul_f32 v[34:35], v[34:35], v[32:33] op_sel_hi:[1,0]
	v_pk_mul_f32 v[26:27], v[26:27], v[32:33] op_sel_hi:[1,0]
	v_and_b32_e32 v53, 0xffff0000, v20
	v_lshlrev_b32_e32 v20, 16, v21
	v_and_b32_e32 v21, 0xffff0000, v21
	v_pk_fma_f32 v[6:7], v[10:11], v[28:29], v[6:7]
	v_pk_fma_f32 v[8:9], v[12:13], v[30:31], v[8:9]
	v_pk_fma_f32 v[2:3], v[2:3], v[34:35], v[14:15]
	v_pk_fma_f32 v[4:5], v[4:5], v[26:27], v[16:17]
	v_lshlrev_b32_e32 v44, 16, v22
	v_and_b32_e32 v45, 0xffff0000, v22
	v_lshlrev_b32_e32 v22, 16, v23
	v_and_b32_e32 v23, 0xffff0000, v23
	v_lshlrev_b32_e32 v50, 16, v24
	v_and_b32_e32 v51, 0xffff0000, v24
	v_lshlrev_b32_e32 v24, 16, v25
	v_and_b32_e32 v25, 0xffff0000, v25
	v_pk_fma_f32 v[6:7], v[0:1], v[46:47], v[6:7] op_sel_hi:[0,1,1]
	v_pk_fma_f32 v[8:9], v[0:1], v[18:19], v[8:9] op_sel_hi:[0,1,1]
	v_pk_fma_f32 v[2:3], v[0:1], v[52:53], v[2:3] op_sel_hi:[0,1,1]
	v_pk_fma_f32 v[4:5], v[0:1], v[20:21], v[4:5] op_sel_hi:[0,1,1]
	v_pk_mul_f32 v[6:7], v[6:7], v[44:45]
	v_pk_mul_f32 v[8:9], v[8:9], v[22:23]
	v_pk_mul_f32 v[10:11], v[2:3], v[50:51]
	v_pk_mul_f32 v[12:13], v[4:5], v[24:25]
	v_cvt_pk_bf16_f32 v2, v6, v7
	v_cvt_pk_bf16_f32 v3, v8, v9
	v_cvt_pk_bf16_f32 v4, v10, v11
	v_cvt_pk_bf16_f32 v5, v12, v13
	flat_store_dwordx4 v[38:39], v[2:5] offset:1024
	v_lshlrev_b32_e32 v102, 16, v90
	v_and_b32_e32 v103, 0xffff0000, v90
	v_pk_add_f32 v[94:95], v[94:95], v[96:97]
	v_lshlrev_b32_e32 v90, 16, v91
	v_pk_add_f32 v[86:87], v[94:95], v[86:87]
	v_and_b32_e32 v91, 0xffff0000, v91
	v_pk_add_f32 v[86:87], v[88:89], v[86:87]
	v_lshlrev_b32_e32 v108, 16, v92
	v_pk_mul_f32 v[86:87], v[86:87], s[22:23] op_sel_hi:[1,0]
	v_and_b32_e32 v109, 0xffff0000, v92
	v_lshlrev_b32_e32 v92, 16, v93
	v_and_b32_e32 v93, 0xffff0000, v93
	v_fma_f32 v96, -v86, v86, v87
	v_pk_add_f32 v[88:89], v[102:103], v[86:87] op_sel_hi:[1,0] neg_lo:[0,1] neg_hi:[0,1]
	v_pk_add_f32 v[90:91], v[90:91], v[86:87] op_sel_hi:[1,0] neg_lo:[0,1] neg_hi:[0,1]
	v_pk_add_f32 v[94:95], v[108:109], v[86:87] op_sel_hi:[1,0] neg_lo:[0,1] neg_hi:[0,1]
	v_pk_add_f32 v[86:87], v[92:93], v[86:87] op_sel_hi:[1,0] neg_lo:[0,1] neg_hi:[0,1]
	v_max_f32_e32 v92, 0, v96
	v_add_f32_e32 v92, 0x3a27c5ac, v92
	v_mul_f32_e32 v93, 0x4b800000, v92
	v_cmp_gt_f32_e32 vcc, s40, v92
	v_lshlrev_b32_e32 v106, 16, v78
	v_and_b32_e32 v107, 0xffff0000, v78
	v_cndmask_b32_e32 v92, v92, v93, vcc
	v_rsq_f32_e32 v92, v92
	v_lshlrev_b32_e32 v78, 16, v79
	v_and_b32_e32 v79, 0xffff0000, v79
	v_lshlrev_b32_e32 v112, 16, v80
	v_mul_f32_e32 v93, 0x45800000, v92
	v_cndmask_b32_e32 v92, v92, v93, vcc
	v_pk_mul_f32 v[88:89], v[88:89], v[92:93] op_sel_hi:[1,0]
	v_pk_mul_f32 v[90:91], v[90:91], v[92:93] op_sel_hi:[1,0]
	v_pk_mul_f32 v[94:95], v[94:95], v[92:93] op_sel_hi:[1,0]
	v_pk_mul_f32 v[86:87], v[86:87], v[92:93] op_sel_hi:[1,0]
	v_and_b32_e32 v113, 0xffff0000, v80
	v_lshlrev_b32_e32 v80, 16, v81
	v_and_b32_e32 v81, 0xffff0000, v81
	v_pk_fma_f32 v[66:67], v[70:71], v[88:89], v[66:67]
	v_pk_fma_f32 v[68:69], v[72:73], v[90:91], v[68:69]
	v_pk_fma_f32 v[62:63], v[62:63], v[94:95], v[74:75]
	v_pk_fma_f32 v[64:65], v[64:65], v[86:87], v[76:77]
	v_lshlrev_b32_e32 v104, 16, v82
	v_and_b32_e32 v105, 0xffff0000, v82
	v_lshlrev_b32_e32 v82, 16, v83
	v_and_b32_e32 v83, 0xffff0000, v83
	v_lshlrev_b32_e32 v110, 16, v84
	v_and_b32_e32 v111, 0xffff0000, v84
	v_lshlrev_b32_e32 v84, 16, v85
	v_and_b32_e32 v85, 0xffff0000, v85
	v_pk_fma_f32 v[66:67], v[60:61], v[106:107], v[66:67] op_sel_hi:[0,1,1]
	v_pk_fma_f32 v[68:69], v[60:61], v[78:79], v[68:69] op_sel_hi:[0,1,1]
	v_pk_fma_f32 v[62:63], v[60:61], v[112:113], v[62:63] op_sel_hi:[0,1,1]
	v_pk_fma_f32 v[64:65], v[60:61], v[80:81], v[64:65] op_sel_hi:[0,1,1]
	v_pk_mul_f32 v[66:67], v[66:67], v[104:105]
	v_pk_mul_f32 v[68:69], v[68:69], v[82:83]
	v_pk_mul_f32 v[70:71], v[62:63], v[110:111]
	v_pk_mul_f32 v[72:73], v[64:65], v[84:85]
	v_cvt_pk_bf16_f32 v62, v66, v67
	v_cvt_pk_bf16_f32 v63, v68, v69
	v_cvt_pk_bf16_f32 v64, v70, v71
	v_cvt_pk_bf16_f32 v65, v72, v73
	flat_store_dwordx4 v[98:99], v[62:65] offset:1024
	s_andn2_b64 exec, exec, s[20:21]
	s_cbranch_execnz .LBB0_965
